# kernel-start grid sync: L2 write-back only in workgroup 0 (the only one that stored before it)
# speedup vs baseline: 1.0077x; 1.0007x over previous
.LBB0_14:
	v_lshrrev_b32_e32 v1, 20, v0
	v_lshrrev_b32_e32 v0, 10, v0
	v_or_b32_e32 v0, v0, v1
	s_movk_i32 s6, 0x3ff
	v_and_or_b32 v0, v0, s6, v208
	v_cmp_eq_u32_e32 vcc, 0, v0
	s_waitcnt lgkmcnt(0)
	s_barrier
	s_and_saveexec_b64 s[6:7], vcc
	s_cbranch_execz .LBB0_24
	s_cmp_lg_u32 s2, 0
	s_cbranch_scc1 .Lgs_nowb
	buffer_wbl2 sc1
.Lgs_nowb:
	s_waitcnt vmcnt(0)
	s_load_dwordx2 s[8:9], s[8:9], 0x58
	v_mov_b32_e32 v2, 0
	s_mov_b64 s[10:11], exec
	v_mbcnt_lo_u32_b32 v1, s10, 0
	v_mbcnt_hi_u32_b32 v1, s11, v1
	s_waitcnt lgkmcnt(0)
	global_load_dword v0, v2, s[8:9] offset:40
	v_cmp_eq_u32_e32 vcc, 0, v1
	s_and_saveexec_b64 s[12:13], vcc
	s_cbranch_execz .LBB0_17
	s_bcnt1_i32_b64 s10, s[10:11]
	v_mov_b32_e32 v3, s10
	global_atomic_add v3, v2, v3, s[8:9] offset:32 sc0
